# MLA fast loop: K(t+2) loads, pointer increments and all LDS address arithmetic moved from the softmax/PV section into the QK section (shorter instruction stream for the VALU-bound wave)
# speedup vs baseline: 1.0046x; 1.0046x over previous
.Lmf_entry:
	v_mov_b32_e32 v239, 0
	v_lshl_add_u64 v[174:175], s[98:99], 0, v[174:175]
	v_lshl_add_u64 v[176:177], s[98:99], 0, v[176:177]
	v_lshl_add_u64 v[178:179], s[78:79], 0, v[178:179]
	v_lshl_add_u64 v[180:181], s[78:79], 0, v[180:181]
	v_lshl_add_u64 v[182:183], s[78:79], 0, v[182:183]
	s_mov_b32 s12, 0
	s_mov_b32 s0, 0xac00
	global_load_dwordx4 v[240:243], v[174:175], off offset:256
	global_load_dwordx4 v[244:247], v[176:177], off offset:256
.Lmf_loop:
	s_setprio 0
	v_add3_u32 v131, s12, v132, v204
	ds_read_b128 v[122:125], v131
	ds_read_b128 v[126:129], v131 offset:6656
	ds_read_b128 v[184:187], v131 offset:13312
	ds_read_b128 v[208:211], v131 offset:19968
	ds_read_b128 v[212:215], v131 offset:32
	ds_read_b128 v[216:219], v131 offset:6688
	s_waitcnt lgkmcnt(5)
	v_mfma_f32_32x32x16_bf16 v[82:97], v[122:125], v[102:105], 0
	ds_read_b128 v[122:125], v131 offset:13344
	s_waitcnt lgkmcnt(5)
	v_mfma_f32_32x32x16_bf16 v[66:81], v[126:129], v[102:105], 0
	v_add3_u32 v173, s12, v189, v205
	v_add3_u32 v236, s0, v191, v192
	v_add3_u32 v237, s0, v194, v195
	v_add3_u32 v238, s0, v197, v198
	ds_read_b128 v[126:129], v131 offset:20000
	s_waitcnt lgkmcnt(5)
	v_mfma_f32_32x32x16_bf16 v[50:65], v[184:187], v[102:105], 0
	v_add_u32_e32 v155, 0x8900, v173
	v_add_u32_e32 v173, 0x6800, v173
	ds_read_b128 v[184:187], v131 offset:64
	s_waitcnt lgkmcnt(5)
	v_mfma_f32_32x32x16_bf16 v[34:49], v[208:211], v[102:105], 0
	v_add_u32_e32 v220, s0, v200
	v_add3_u32 v221, v220, v202, s44
	v_add3_u32 v220, v220, v203, s44
	ds_read_b128 v[208:211], v131 offset:6720
	s_waitcnt lgkmcnt(5)
	v_mfma_f32_32x32x16_bf16 v[82:97], v[212:215], v[110:113], v[82:97]
	ds_read_b128 v[212:215], v131 offset:13376
	s_waitcnt lgkmcnt(5)
	v_mfma_f32_32x32x16_bf16 v[66:81], v[216:219], v[110:113], v[66:81]
	s_waitcnt vmcnt(2)
	ds_write_b128 v236, v[224:227]
	ds_write_b128 v237, v[228:231]
	ds_write_b128 v238, v[232:235]
	ds_read_b128 v[216:219], v131 offset:20032
	s_waitcnt lgkmcnt(5)
	v_mfma_f32_32x32x16_bf16 v[50:65], v[122:125], v[110:113], v[50:65]
	ds_read_b128 v[122:125], v131 offset:96
	s_waitcnt lgkmcnt(5)
	v_mfma_f32_32x32x16_bf16 v[34:49], v[126:129], v[110:113], v[34:49]
	ds_read_b128 v[126:129], v131 offset:6752
	s_waitcnt lgkmcnt(5)
	v_mfma_f32_32x32x16_bf16 v[82:97], v[184:187], v[98:101], v[82:97]
	global_load_dwordx4 v[224:227], v[182:183], off
	global_load_dwordx4 v[228:231], v[180:181], off
	global_load_dwordx4 v[232:235], v[178:179], off
	ds_read_b128 v[184:187], v131 offset:13408
	s_waitcnt lgkmcnt(5)
	v_mfma_f32_32x32x16_bf16 v[66:81], v[208:211], v[98:101], v[66:81]
	ds_read_b128 v[208:211], v131 offset:20064
	s_waitcnt lgkmcnt(5)
	v_mfma_f32_32x32x16_bf16 v[50:65], v[212:215], v[98:101], v[50:65]
	v_lshl_add_u64 v[178:179], v[178:179], 0, s[8:9]
	v_lshl_add_u64 v[180:181], v[180:181], 0, s[8:9]
	v_lshl_add_u64 v[182:183], v[182:183], 0, s[8:9]
	ds_read_b128 v[212:215], v131 offset:128
	s_waitcnt lgkmcnt(5)
	v_mfma_f32_32x32x16_bf16 v[34:49], v[216:219], v[98:101], v[34:49]
	ds_read_b128 v[216:219], v131 offset:6784
	s_waitcnt lgkmcnt(5)
	v_mfma_f32_32x32x16_bf16 v[82:97], v[122:125], v[106:109], v[82:97]
	v_lshl_add_u64 v[174:175], v[174:175], 0, s[6:7]
	v_lshl_add_u64 v[176:177], v[176:177], 0, s[6:7]
	ds_read_b128 v[122:125], v131 offset:13440
	s_waitcnt lgkmcnt(5)
	v_mfma_f32_32x32x16_bf16 v[66:81], v[126:129], v[106:109], v[66:81]
	ds_read_b128 v[126:129], v131 offset:20096
	s_waitcnt lgkmcnt(5)
	v_mfma_f32_32x32x16_bf16 v[50:65], v[184:187], v[106:109], v[50:65]
	ds_read_b128 v[184:187], v131 offset:160
	s_waitcnt lgkmcnt(5)
	v_mfma_f32_32x32x16_bf16 v[34:49], v[208:211], v[106:109], v[34:49]
	ds_read_b128 v[208:211], v131 offset:6816
	s_waitcnt lgkmcnt(5)
	v_mfma_f32_32x32x16_bf16 v[82:97], v[212:215], v[118:121], v[82:97]
	ds_read_b128 v[212:215], v131 offset:13472
	s_waitcnt lgkmcnt(5)
	v_mfma_f32_32x32x16_bf16 v[66:81], v[216:219], v[118:121], v[66:81]
	ds_read_b128 v[216:219], v131 offset:20128
	s_waitcnt lgkmcnt(5)
	v_mfma_f32_32x32x16_bf16 v[50:65], v[122:125], v[118:121], v[50:65]
	s_waitcnt lgkmcnt(4)
	v_mfma_f32_32x32x16_bf16 v[34:49], v[126:129], v[118:121], v[34:49]
	s_waitcnt lgkmcnt(3)
	v_mfma_f32_32x32x16_bf16 v[82:97], v[184:187], v[114:117], v[82:97]
	s_waitcnt lgkmcnt(2)
	v_mfma_f32_32x32x16_bf16 v[66:81], v[208:211], v[114:117], v[66:81]
	s_waitcnt lgkmcnt(1)
	v_mfma_f32_32x32x16_bf16 v[50:65], v[212:215], v[114:117], v[50:65]
	s_waitcnt lgkmcnt(0)
	v_mfma_f32_32x32x16_bf16 v[34:49], v[216:219], v[114:117], v[34:49]
	s_barrier
	s_setprio 1
	ds_read_b128 v[122:125], v173
	ds_read_b128 v[126:129], v155 offset:256
	ds_read_b128 v[184:187], v173 offset:32
	ds_read_b128 v[208:211], v155 offset:288
	ds_read_b128 v[212:215], v173 offset:64
	ds_read_b128 v[216:219], v155 offset:320
	v_exp_f32_e32 v82, v82
	v_exp_f32_e32 v83, v83
	v_exp_f32_e32 v84, v84
	v_exp_f32_e32 v85, v85
	v_exp_f32_e32 v86, v86
	v_exp_f32_e32 v87, v87
	v_exp_f32_e32 v88, v88
	v_exp_f32_e32 v89, v89
	v_add_f32_e32 v1, v82, v1
	v_add_f32_e32 v239, v83, v239
	v_add_f32_e32 v1, v84, v1
	v_add_f32_e32 v239, v85, v239
	v_add_f32_e32 v1, v86, v1
	v_add_f32_e32 v239, v87, v239
	v_add_f32_e32 v1, v88, v1
	v_add_f32_e32 v239, v89, v239
	v_cvt_pk_bf16_f32 v82, v82, v83
	v_cvt_pk_bf16_f32 v83, v84, v85
	v_cvt_pk_bf16_f32 v84, v86, v87
	v_cvt_pk_bf16_f32 v85, v88, v89
	s_waitcnt lgkmcnt(4)
	v_exp_f32_e32 v90, v90
	v_exp_f32_e32 v91, v91
	v_exp_f32_e32 v92, v92
	v_exp_f32_e32 v93, v93
	v_mfma_f32_32x32x16_bf16 v[18:33], v[122:125], v[82:85], v[18:33]
	v_exp_f32_e32 v94, v94
	v_exp_f32_e32 v95, v95
	v_exp_f32_e32 v96, v96
	v_exp_f32_e32 v97, v97
	v_mfma_f32_32x32x16_bf16 v[2:17], v[126:129], v[82:85], v[2:17]
	ds_read_b128 v[122:125], v173 offset:96
	ds_read_b128 v[126:129], v155 offset:352
	v_add_f32_e32 v1, v90, v1
	v_add_f32_e32 v239, v91, v239
	v_add_f32_e32 v1, v92, v1
	v_add_f32_e32 v239, v93, v239
	v_add_f32_e32 v1, v94, v1
	v_add_f32_e32 v239, v95, v239
	v_add_f32_e32 v1, v96, v1
	v_add_f32_e32 v239, v97, v239
	v_cvt_pk_bf16_f32 v90, v90, v91
	v_cvt_pk_bf16_f32 v91, v92, v93
	v_cvt_pk_bf16_f32 v92, v94, v95
	v_cvt_pk_bf16_f32 v93, v96, v97
	s_waitcnt lgkmcnt(4)
	v_exp_f32_e32 v66, v66
	v_exp_f32_e32 v67, v67
	v_exp_f32_e32 v68, v68
	v_exp_f32_e32 v69, v69
	v_mfma_f32_32x32x16_bf16 v[18:33], v[184:187], v[90:93], v[18:33]
	v_exp_f32_e32 v70, v70
	v_exp_f32_e32 v71, v71
	v_exp_f32_e32 v72, v72
	v_exp_f32_e32 v73, v73
	v_mfma_f32_32x32x16_bf16 v[2:17], v[208:211], v[90:93], v[2:17]
	ds_read_b128 v[184:187], v173 offset:128
	ds_read_b128 v[208:211], v155 offset:384
	v_add_f32_e32 v1, v66, v1
	v_add_f32_e32 v239, v67, v239
	v_add_f32_e32 v1, v68, v1
	v_add_f32_e32 v239, v69, v239
	v_add_f32_e32 v1, v70, v1
	v_add_f32_e32 v239, v71, v239
	v_add_f32_e32 v1, v72, v1
	v_add_f32_e32 v239, v73, v239
	v_cvt_pk_bf16_f32 v66, v66, v67
	v_cvt_pk_bf16_f32 v67, v68, v69
	v_cvt_pk_bf16_f32 v68, v70, v71
	v_cvt_pk_bf16_f32 v69, v72, v73
	s_waitcnt lgkmcnt(4)
	v_exp_f32_e32 v74, v74
	v_exp_f32_e32 v75, v75
	v_exp_f32_e32 v76, v76
	v_exp_f32_e32 v77, v77
	v_mfma_f32_32x32x16_bf16 v[18:33], v[212:215], v[66:69], v[18:33]
	v_exp_f32_e32 v78, v78
	v_exp_f32_e32 v79, v79
	v_exp_f32_e32 v80, v80
	v_exp_f32_e32 v81, v81
	v_mfma_f32_32x32x16_bf16 v[2:17], v[216:219], v[66:69], v[2:17]
	ds_read_b128 v[212:215], v173 offset:160
	ds_read_b128 v[216:219], v155 offset:416
	v_add_f32_e32 v1, v74, v1
	v_add_f32_e32 v239, v75, v239
	v_add_f32_e32 v1, v76, v1
	v_add_f32_e32 v239, v77, v239
	v_add_f32_e32 v1, v78, v1
	v_add_f32_e32 v239, v79, v239
	v_add_f32_e32 v1, v80, v1
	v_add_f32_e32 v239, v81, v239
	v_cvt_pk_bf16_f32 v74, v74, v75
	v_cvt_pk_bf16_f32 v75, v76, v77
	v_cvt_pk_bf16_f32 v76, v78, v79
	v_cvt_pk_bf16_f32 v77, v80, v81
	s_waitcnt lgkmcnt(4)
	v_exp_f32_e32 v50, v50
	v_exp_f32_e32 v51, v51
	v_exp_f32_e32 v52, v52
	v_exp_f32_e32 v53, v53
	v_mfma_f32_32x32x16_bf16 v[18:33], v[122:125], v[74:77], v[18:33]
	v_exp_f32_e32 v54, v54
	v_exp_f32_e32 v55, v55
	v_exp_f32_e32 v56, v56
	v_exp_f32_e32 v57, v57
	v_mfma_f32_32x32x16_bf16 v[2:17], v[126:129], v[74:77], v[2:17]
	ds_read_b128 v[122:125], v173 offset:192
	ds_read_b128 v[126:129], v155 offset:448
	v_add_f32_e32 v1, v50, v1
	v_add_f32_e32 v239, v51, v239
	v_add_f32_e32 v1, v52, v1
	v_add_f32_e32 v239, v53, v239
	v_add_f32_e32 v1, v54, v1
	v_add_f32_e32 v239, v55, v239
	v_add_f32_e32 v1, v56, v1
	v_add_f32_e32 v239, v57, v239
	v_cvt_pk_bf16_f32 v50, v50, v51
	v_cvt_pk_bf16_f32 v51, v52, v53
	v_cvt_pk_bf16_f32 v52, v54, v55
	v_cvt_pk_bf16_f32 v53, v56, v57
	s_waitcnt lgkmcnt(4)
	v_exp_f32_e32 v58, v58
	v_exp_f32_e32 v59, v59
	v_exp_f32_e32 v60, v60
	v_exp_f32_e32 v61, v61
	v_mfma_f32_32x32x16_bf16 v[18:33], v[184:187], v[50:53], v[18:33]
	v_exp_f32_e32 v62, v62
	v_exp_f32_e32 v63, v63
	v_exp_f32_e32 v64, v64
	v_exp_f32_e32 v65, v65
	v_mfma_f32_32x32x16_bf16 v[2:17], v[208:211], v[50:53], v[2:17]
	ds_read_b128 v[184:187], v173 offset:224
	ds_read_b128 v[208:211], v155 offset:480
	v_add_f32_e32 v1, v58, v1
	v_add_f32_e32 v239, v59, v239
	v_add_f32_e32 v1, v60, v1
	v_add_f32_e32 v239, v61, v239
	v_add_f32_e32 v1, v62, v1
	v_add_f32_e32 v239, v63, v239
	v_add_f32_e32 v1, v64, v1
	v_add_f32_e32 v239, v65, v239
	v_cvt_pk_bf16_f32 v58, v58, v59
	v_cvt_pk_bf16_f32 v59, v60, v61
	v_cvt_pk_bf16_f32 v60, v62, v63
	v_cvt_pk_bf16_f32 v61, v64, v65
	s_waitcnt lgkmcnt(4)
	v_exp_f32_e32 v34, v34
	v_exp_f32_e32 v35, v35
	v_exp_f32_e32 v36, v36
	v_exp_f32_e32 v37, v37
	v_mfma_f32_32x32x16_bf16 v[18:33], v[212:215], v[58:61], v[18:33]
	v_exp_f32_e32 v38, v38
	v_exp_f32_e32 v39, v39
	v_exp_f32_e32 v40, v40
	v_exp_f32_e32 v41, v41
	v_mfma_f32_32x32x16_bf16 v[2:17], v[216:219], v[58:61], v[2:17]
	v_add_f32_e32 v1, v34, v1
	v_add_f32_e32 v239, v35, v239
	v_add_f32_e32 v1, v36, v1
	v_add_f32_e32 v239, v37, v239
	v_add_f32_e32 v1, v38, v1
	v_add_f32_e32 v239, v39, v239
	v_add_f32_e32 v1, v40, v1
	v_add_f32_e32 v239, v41, v239
	v_cvt_pk_bf16_f32 v34, v34, v35
	v_cvt_pk_bf16_f32 v35, v36, v37
	v_cvt_pk_bf16_f32 v36, v38, v39
	v_cvt_pk_bf16_f32 v37, v40, v41
	s_waitcnt lgkmcnt(2)
	v_exp_f32_e32 v42, v42
	v_exp_f32_e32 v43, v43
	v_exp_f32_e32 v44, v44
	v_exp_f32_e32 v45, v45
	v_mfma_f32_32x32x16_bf16 v[18:33], v[122:125], v[34:37], v[18:33]
	v_exp_f32_e32 v46, v46
	v_exp_f32_e32 v47, v47
	v_exp_f32_e32 v48, v48
	v_exp_f32_e32 v49, v49
	v_mfma_f32_32x32x16_bf16 v[2:17], v[126:129], v[34:37], v[2:17]
	v_add_f32_e32 v1, v42, v1
	v_add_f32_e32 v239, v43, v239
	v_add_f32_e32 v1, v44, v1
	v_add_f32_e32 v239, v45, v239
	v_add_f32_e32 v1, v46, v1
	v_add_f32_e32 v239, v47, v239
	v_add_f32_e32 v1, v48, v1
	v_add_f32_e32 v239, v49, v239
	v_cvt_pk_bf16_f32 v42, v42, v43
	v_cvt_pk_bf16_f32 v43, v44, v45
	v_cvt_pk_bf16_f32 v44, v46, v47
	v_cvt_pk_bf16_f32 v45, v48, v49
	s_waitcnt lgkmcnt(0)
	s_nop 0
	v_mfma_f32_32x32x16_bf16 v[18:33], v[184:187], v[42:45], v[18:33]
	v_mfma_f32_32x32x16_bf16 v[2:17], v[208:211], v[42:45], v[2:17]
	s_add_i32 s13, s13, 1
	s_waitcnt vmcnt(3)
	ds_write2_b64 v221, v[240:241], v[242:243] offset1:2
	ds_write2_b64 v220, v[244:245], v[246:247] offset1:2
	s_cmp_eq_u32 s34, s13
	s_waitcnt lgkmcnt(0)
	global_load_dwordx4 v[240:243], v[174:175], off offset:256
	global_load_dwordx4 v[244:247], v[176:177], off offset:256
	s_barrier
	s_cbranch_scc1 .Lmf_final
	s_xor_b32 s0, s0, 0xac00
	s_xor_b32 s12, s12, 0xac00
	s_branch .Lmf_loop
